# W_up/W_dn/W_out/W_branch f32->bf16 conversions moved out of P0 into the attention work queue as extra units (every 4th of the first 640 entries), overlapping HBM streaming with attention compute; plus
# speedup vs baseline: 1.0328x; 1.0239x over previous
; #define LAS __attribute__((address_space(3)))
; #define IN_cvec PTRF(1)
; #define IN_w_ada PTRF(2)
; __global__ void __launch_bounds__(512, 2) fwd_kernel(Args a) {
;     ...
;     if (IN(0)) for (int rep = 0; rep < REPS(0); ++rep) { DECL_WS();
;         const float* const wada_p = IN_w_ada; const float* const c_p = IN_cvec;
;         LAS float* scr = (LAS float*)(lds + wave * 16640);
;         constexpr int I_ADA = 48 * KC_ADA, I_IN = 32 * 128, I_UP = 32 * 128, I_DN = 128 * 32, I_OUT = 32 * 32, I_BR = 16 * 32, I_Q = 8 * 24, I_KV = 4 * 32;
;         constexpr int NITEMS = I_ADA + I_IN + I_UP + I_DN + I_OUT + 2 * I_BR + I_Q + I_KV;
;         for (int it = gw; it < NITEMS; it += NGW) {
;             int r = it;
.LBB0_21:
	s_lshr_b32 s50, s28, 6
	s_lshl_b32 s0, s93, 3
	s_add_i32 s96, s50, s0
	s_lshl_b32 s14, s92, 3
	s_cmp_lt_i32 s90, 1
	s_cselect_b64 s[0:1], -1, 0
	s_cmp_gt_i32 s91, 0
	s_cselect_b64 s[2:3], -1, 0
	s_and_b64 s[8:9], s[0:1], s[2:3]
	v_writelane_b32 v255, s68, 3
	v_and_b32_e32 v196, 63, v0
	s_andn2_b64 vcc, exec, s[8:9]
	v_lshlrev_b32_e32 v1, 1, v0
	v_writelane_b32 v255, s69, 4
	s_cbranch_vccnz .LBB0_221
	s_mov_b32 s100, 0
	s_mov_b32 s99, s96
	s_movk_i32 s101, 0x15ff
.Lp0_entry:
	s_add_i32 s0, 0, 0x220a0
	s_add_i32 s1, 0, 0x22008
	v_mov_b32_e32 v2, s0
	ds_read_b64 v[6:7], v2
	v_mov_b32_e32 v2, s1
	ds_read2_b64 v[2:5], v2 offset1:1
	s_cmpk_gt_i32 s96, 0x3f3f
	s_waitcnt lgkmcnt(1)
	v_readfirstlane_b32 s4, v6
	v_readfirstlane_b32 s5, v7
	s_waitcnt lgkmcnt(0)
	v_readfirstlane_b32 s0, v4
	v_readfirstlane_b32 s1, v5
	v_readfirstlane_b32 s15, v2
	v_readfirstlane_b32 s16, v3
	s_cbranch_scc1 .LBB0_209
	v_lshlrev_b32_e32 v2, 2, v0
	v_lshrrev_b32_e32 v94, 4, v196
	v_and_b32_e32 v95, 60, v2
	s_movk_i32 s3, 0x104
	v_mov_b32_e32 v2, 0x410
	v_mad_u32_u24 v98, v94, s3, v2
	v_mov_b32_e32 v2, 0x820
	v_mad_u32_u24 v99, v94, s3, v2
	v_mov_b32_e32 v2, 0x1040
	v_mad_u32_u24 v100, v94, s3, v2
	v_mov_b32_e32 v2, 0x1860
	v_mad_u32_u24 v101, v94, s3, v2
	v_lshlrev_b32_e32 v2, 3, v0
	s_mul_i32 s2, s50, 0x4100
	v_lshrrev_b32_e32 v102, 3, v196
	v_and_b32_e32 v2, 56, v2
	s_add_i32 s2, s2, 0
	v_mul_u32_u24_e32 v3, 0x104, v2
	v_lshlrev_b32_e32 v4, 2, v102
	v_add3_u32 v103, s2, v3, v4
	v_lshlrev_b32_e32 v3, 5, v0
	v_and_b32_e32 v3, 32, v3
	v_and_or_b32 v3, v1, 28, v3
	v_lshl_add_u32 v96, v95, 2, s2
	v_add_u32_e32 v111, 0xf10, v3
	v_lshlrev_b32_e32 v2, 1, v2
	v_mov_b32_e32 v3, 0
	v_mad_u32_u24 v97, v94, s3, v96
	v_lshl_add_u64 v[4:5], s[4:5], 0, v[2:3]
	s_mov_b64 s[2:3], 0x7a00000
	v_lshl_add_u64 v[74:75], v[4:5], 0, s[2:3]
	s_mov_b64 s[2:3], 0x7800000
	v_lshl_add_u64 v[76:77], v[4:5], 0, s[2:3]
	s_mov_b64 s[2:3], 0x7400000
	v_lshl_add_u64 v[78:79], v[4:5], 0, s[2:3]
	s_mov_b64 s[2:3], 0x7000000
	v_lshl_add_u64 v[80:81], v[4:5], 0, s[2:3]
	s_mov_b64 s[2:3], 0x6800000
	s_add_u32 s17, s4, 0x15400000
	v_lshl_add_u64 v[82:83], v[4:5], 0, s[2:3]
	s_mov_b64 s[2:3], 0x4800000
	s_addc_u32 s18, s5, 0
	v_lshl_add_u64 v[84:85], v[4:5], 0, s[2:3]
	s_mov_b64 s[2:3], 0x2800000
	v_lshl_add_u64 v[86:87], v[4:5], 0, s[2:3]
	s_mov_b64 s[2:3], 0x800000
	s_add_u32 s19, s0, 0xb4000
	s_mov_b32 s7, 0
	v_or_b32_e32 v104, 8, v102
	v_or_b32_e32 v105, 16, v102
	v_or_b32_e32 v106, 24, v102
	v_or_b32_e32 v107, 32, v102
	v_or_b32_e32 v108, 40, v102
	v_or_b32_e32 v109, 48, v102
	v_or_b32_e32 v110, 56, v102
	v_lshlrev_b32_e32 v112, 2, v196
	v_lshl_add_u64 v[88:89], v[4:5], 0, s[2:3]
	s_addc_u32 s20, s1, 0
	s_add_i32 s21, 0, 0x22040
	s_mov_b32 s22, 0x8000
	s_mov_b32 s23, 0x10000
	s_mov_b32 s24, 0x18000
	s_mov_b32 s25, 0x20000
	s_mov_b32 s26, 0x28000
	s_mov_b32 s27, 0x30000
	s_mov_b32 s28, 0x38000
	s_mov_b32 s29, 0x40000
	s_mov_b32 s30, 0x48000
	s_mov_b32 s31, 0x50000
	s_mov_b32 s34, 0x58000
	s_mov_b32 s35, 0x60000
	s_mov_b32 s36, 0x68000
	s_mov_b32 s37, 0x70000
	s_mov_b32 s38, 0x78000
	s_movk_i32 s39, 0x7fff
	s_mov_b32 s40, 0xffff0000
	s_add_i32 s41, 0, 0x22030
	s_movk_i32 s42, 0x7f
	s_movk_i32 s43, 0x80
	s_add_i32 s44, 0, 0x22058
	s_add_i32 s45, 0, 0x22050
	s_add_i32 s46, 0, 0x22060
	s_add_i32 s47, 0, 0x22080
	s_add_i32 s48, 0, 0x22078
	s_mov_b32 s49, 0x80000
	s_mov_b32 s51, 0xa0000
	s_mov_b32 s52, 0xc0000
	s_mov_b32 s53, 0xe0000
	s_mov_b32 s54, 0x100000
	s_mov_b32 s55, 0x120000
	s_mov_b32 s56, 0x140000
	s_mov_b32 s57, 0x160000
	s_mov_b32 s58, 0x180000
	s_mov_b32 s59, 0x1a0000
	s_mov_b32 s60, 0x1c0000
	s_mov_b32 s61, 0x1e0000
	s_add_i32 s62, 0, 0x22020
	s_movk_i32 s63, 0xf0f
	s_movk_i32 s64, 0x1f50
	v_mov_b32_e32 v113, 0x2000
	s_mov_b32 s65, 0xfff58000
	s_mov_b32 s66, 0xfff64000
	s_mov_b32 s67, 0xfff70000
	s_mov_b32 s68, 0xfff7c000
	s_mov_b32 s69, 0xfff88000
	s_mov_b32 s70, 0xfff94000
	s_mov_b32 s71, 0xfffa0000
	s_mov_b32 s72, 0xfffac000
	s_mov_b32 s73, 0xfffb8000
	s_mov_b32 s74, 0xfffc4000
	s_mov_b32 s75, 0xfffd0000
	s_mov_b32 s76, 0xfffdc000
	s_mov_b32 s77, 0xfffe8000
	s_mov_b32 s78, 0xffff4000
	s_mov_b64 s[10:11], 0xc0000
	s_mov_b32 s79, s99
	s_branch .LBB0_25
.LBB0_24:
	s_add_i32 s79, s79, s14
	s_cmp_gt_i32 s79, s101
	s_cbranch_scc1 .LBB0_209

; __device__ __forceinline__ float sigmoidf_(float x) { return __builtin_amdgcn_rcpf(1.0f + __builtin_amdgcn_exp2f(-1.4426950408889634f * x)); }
; #define IN_w_in PTRF(4)
; __global__ void __launch_bounds__(512, 2) fwd_kernel(Args a) {
;     ...
;         for (int it = gw; it < NITEMS; it += NGW) {
;             int r = it;
;             if (r < I_ADA) {
;                 const int cb = r % 48, kc = r / 48, col = cb * 256 + lane * 4;
;                 f32x4 s0 = {0.f, 0.f, 0.f, 0.f}, s1 = {0.f, 0.f, 0.f, 0.f};
;                 const int kbeg = kc * (DMODEL / KC_ADA);
; #pragma unroll 16
;                 for (int k = kbeg; k < kbeg + DMODEL / KC_ADA; ++k) {
;                     const f32x4 wv = __builtin_nontemporal_load((const f32x4*)(wada_p + (size_t)k * NADA + col));
;                     const float c0 = c_p[k], c1 = c_p[DMODEL + k];
;                     const float a0 = c0 * sigmoidf_(c0), a1 = c1 * sigmoidf_(c1);
;                     s0 += wv * a0; s1 += wv * a1;
;                 }
;                 *(f32x4*)(part + (size_t)(kc * 2 + 0) * NADA + col) = s0; *(f32x4*)(part + (size_t)(kc * 2 + 1) * NADA + col) = s1;
;                 continue;
;             }
;             r -= I_ADA;
;             if (r < I_IN) { conv_item(IN_w_in, 2048, DIN, WinT, scr, r / 128, r % 128, lane, nullptr, map_win); continue; } r -= I_IN;
;             if (r < I_UP) { conv_item(IN_w_up, 2048, DFF, WupT, scr, r / 128, r % 128, lane, nullptr, map_id, true); continue; } r -= I_UP;
;             if (r < I_DN) { conv_item(IN_w_dn, 8192, DMODEL, WdnT, scr, r / 32, r % 32, lane, nullptr, map_id, true); continue; } r -= I_DN;
;             if (r < I_OUT) { conv_item(IN_w_out, 2048, DMODEL, WoutT, scr, r / 32, r % 32, lane, nullptr, map_id, true); continue; } r -= I_OUT;
;             if (r < I_BR) { conv_item(IN_w_bf, 1024, DMODEL, WbrT, scr, r / 32, r % 32, lane, nullptr, map_id, true); continue; } r -= I_BR;
;             if (r < I_BR) { conv_item(IN_w_bm, 1024, DMODEL, WbrT + (size_t)2048 * 1024, scr, r / 32, r % 32, lane, nullptr, map_id, true); continue; } r -= I_BR;
;             if (r < I_Q) { conv_item(IN_w_q, 512, QW, WqT, scr, r / 24, r % 24, lane, IN_g_q, map_wq); continue; } r -= I_Q;
;             conv_item(IN_w_kv, 256, KVW, WkvT, scr, r / 32, r % 32, lane, IN_g_kv, map_id);
;         }
;         for (int e = bx * 512 + tid; e < SEQ * 32; e += G * 512) {
.LBB0_209:
	s_cmp_eq_u32 s100, 1
	s_cbranch_scc1 .Lcv_ret
	s_cmp_eq_u32 s100, 2
	s_cbranch_scc1 .Lp0_rope
	s_mov_b32 s100, 2
	s_add_i32 s99, s96, 0x3e00
	s_movk_i32 s101, 0x3f3f
	s_cmp_gt_i32 s99, s101
	s_cbranch_scc1 .Lp0_rope
	s_branch .Lp0_entry

; #define IN_w_in PTRF(4)
; #define IN_g_q PTRF(6)
; __global__ void __launch_bounds__(512, 2) fwd_kernel(Args a) {
;     ...
;         for (int it = gw; it < NITEMS; it += NGW) {
;             int r = it;
;             if (r < I_ADA) {
;                 const int cb = r % 48, kc = r / 48, col = cb * 256 + lane * 4;
;                 f32x4 s0 = {0.f, 0.f, 0.f, 0.f}, s1 = {0.f, 0.f, 0.f, 0.f};
;                 const int kbeg = kc * (DMODEL / KC_ADA);
; #pragma unroll 16
;                 for (int k = kbeg; k < kbeg + DMODEL / KC_ADA; ++k) {
;                     const f32x4 wv = __builtin_nontemporal_load((const f32x4*)(wada_p + (size_t)k * NADA + col));
;                     const float c0 = c_p[k], c1 = c_p[DMODEL + k];
;                     const float a0 = c0 * sigmoidf_(c0), a1 = c1 * sigmoidf_(c1);
;                     s0 += wv * a0; s1 += wv * a1;
;                 }
;                 *(f32x4*)(part + (size_t)(kc * 2 + 0) * NADA + col) = s0; *(f32x4*)(part + (size_t)(kc * 2 + 1) * NADA + col) = s1;
;                 continue;
;             }
;             r -= I_ADA;
;             if (r < I_IN) { conv_item(IN_w_in, 2048, DIN, WinT, scr, r / 128, r % 128, lane, nullptr, map_win); continue; } r -= I_IN;
;             if (r < I_UP) { conv_item(IN_w_up, 2048, DFF, WupT, scr, r / 128, r % 128, lane, nullptr, map_id, true); continue; } r -= I_UP;
;             if (r < I_DN) { conv_item(IN_w_dn, 8192, DMODEL, WdnT, scr, r / 32, r % 32, lane, nullptr, map_id, true); continue; } r -= I_DN;
;             if (r < I_OUT) { conv_item(IN_w_out, 2048, DMODEL, WoutT, scr, r / 32, r % 32, lane, nullptr, map_id, true); continue; } r -= I_OUT;
;             if (r < I_BR) { conv_item(IN_w_bf, 1024, DMODEL, WbrT, scr, r / 32, r % 32, lane, nullptr, map_id, true); continue; } r -= I_BR;
;             if (r < I_BR) { conv_item(IN_w_bm, 1024, DMODEL, WbrT + (size_t)2048 * 1024, scr, r / 32, r % 32, lane, nullptr, map_id, true); continue; } r -= I_BR;
;             if (r < I_Q) { conv_item(IN_w_q, 512, QW, WqT, scr, r / 24, r % 24, lane, IN_g_q, map_wq); continue; } r -= I_Q;
;     ...
;         for (;;) {
;             if (tid == 0) *qw = atomicAdd(ctl + 64 * rep, 1u);
;             __syncthreads();
;             const unsigned idx = *qw;
;             __syncthreads();
;             if (idx >= 768u) break;
;             const int level = idx / 48, rr = idx % 48, qb = 15 - level;
.LBB0_642:
	s_andn2_b64 vcc, exec, s[0:1]
	s_cbranch_vccz .LBB0_733
	s_branch .LBB0_643
.Lcv_unit:
	s_lshl_b32 s0, s1, 6
	s_addk_i32 s0, 0x1600
	v_readfirstlane_b32 s1, v0
	s_lshr_b32 s1, s1, 6
	s_add_i32 s99, s0, s1
	s_add_i32 s101, s0, 63
	v_writelane_b32 v248, s2, 0
	v_writelane_b32 v248, s3, 1
	v_writelane_b32 v248, s4, 2
	v_writelane_b32 v248, s5, 3
	v_writelane_b32 v248, s6, 4
	v_writelane_b32 v248, s7, 5
	v_writelane_b32 v248, s8, 6
	v_writelane_b32 v248, s9, 7
	v_writelane_b32 v248, s10, 8
	v_writelane_b32 v248, s11, 9
	v_writelane_b32 v248, s12, 10
	v_writelane_b32 v248, s13, 11
	v_writelane_b32 v248, s14, 12
	v_writelane_b32 v248, s15, 13
	v_writelane_b32 v248, s16, 14
	v_writelane_b32 v248, s17, 15
	v_writelane_b32 v248, s18, 16
	v_writelane_b32 v248, s19, 17
	v_writelane_b32 v248, s20, 18
	v_writelane_b32 v248, s21, 19
	v_writelane_b32 v248, s22, 20
	v_writelane_b32 v248, s23, 21
	v_writelane_b32 v248, s24, 22
	v_writelane_b32 v248, s25, 23
	v_writelane_b32 v248, s26, 24
	v_writelane_b32 v248, s27, 25
	v_writelane_b32 v248, s28, 26
	v_writelane_b32 v248, s29, 27
	v_writelane_b32 v248, s30, 28
	v_writelane_b32 v248, s31, 29
	v_writelane_b32 v248, s32, 30
	v_writelane_b32 v248, s33, 31
	v_writelane_b32 v248, s34, 32
	v_writelane_b32 v248, s35, 33
	v_writelane_b32 v248, s36, 34
	v_writelane_b32 v248, s37, 35
	v_writelane_b32 v248, s38, 36
	v_writelane_b32 v248, s39, 37
	v_writelane_b32 v248, s40, 38
	v_writelane_b32 v248, s41, 39
	v_writelane_b32 v248, s42, 40
	v_writelane_b32 v248, s43, 41
	v_writelane_b32 v248, s44, 42
	v_writelane_b32 v248, s45, 43
	v_writelane_b32 v248, s46, 44
	v_writelane_b32 v248, s47, 45
	v_writelane_b32 v248, s48, 46
	v_writelane_b32 v248, s49, 47
	v_writelane_b32 v248, s50, 48
	v_writelane_b32 v248, s51, 49
	v_writelane_b32 v248, s52, 50
	v_writelane_b32 v248, s53, 51
	v_writelane_b32 v248, s54, 52
	v_writelane_b32 v248, s55, 53
	v_writelane_b32 v248, s56, 54
	v_writelane_b32 v248, s57, 55
	v_writelane_b32 v248, s58, 56
	v_writelane_b32 v248, s59, 57
	v_writelane_b32 v248, s60, 58
	v_writelane_b32 v248, s61, 59
	v_writelane_b32 v248, s62, 60
	v_writelane_b32 v248, s63, 61
	v_writelane_b32 v248, s64, 62
	v_writelane_b32 v248, s65, 63
	v_writelane_b32 v249, s66, 0
	v_writelane_b32 v249, s67, 1
	v_writelane_b32 v249, s68, 2
	v_writelane_b32 v249, s69, 3
	v_writelane_b32 v249, s70, 4
	v_writelane_b32 v249, s71, 5
	v_writelane_b32 v249, s72, 6
	v_writelane_b32 v249, s73, 7
	v_writelane_b32 v249, s74, 8
	v_writelane_b32 v249, s75, 9
	v_writelane_b32 v249, s76, 10
	v_writelane_b32 v249, s77, 11
	v_writelane_b32 v249, s78, 12
	v_writelane_b32 v249, s79, 13
	v_writelane_b32 v249, s80, 14
	v_mov_b32_e32 v236, v146
	v_mov_b32_e32 v237, v147
	v_mov_b32_e32 v238, v148
	v_mov_b32_e32 v239, v149
	v_mov_b32_e32 v240, v150
	v_mov_b32_e32 v241, v151
	v_mov_b32_e32 v242, v152
	v_mov_b32_e32 v243, v153
	v_mov_b32_e32 v244, v154
	v_mov_b32_e32 v245, v155
	v_mov_b32_e32 v246, v156
	v_mov_b32_e32 v247, v167
	s_mov_b32 s50, s1
	s_mov_b32 s14, 8
	s_mov_b32 s100, 1
	s_branch .Lp0_entry
.Lcv_ret:
	v_mov_b32_e32 v146, v236
	v_mov_b32_e32 v147, v237
	v_mov_b32_e32 v148, v238
	v_mov_b32_e32 v149, v239
	v_mov_b32_e32 v150, v240
	v_mov_b32_e32 v151, v241
	v_mov_b32_e32 v152, v242
	v_mov_b32_e32 v153, v243
	v_mov_b32_e32 v154, v244
	v_mov_b32_e32 v155, v245
	v_mov_b32_e32 v156, v246
	v_mov_b32_e32 v167, v247
	v_readlane_b32 s2, v248, 0
	v_readlane_b32 s3, v248, 1
	v_readlane_b32 s4, v248, 2
	v_readlane_b32 s5, v248, 3
	v_readlane_b32 s6, v248, 4
	v_readlane_b32 s7, v248, 5
	v_readlane_b32 s8, v248, 6
	v_readlane_b32 s9, v248, 7
	v_readlane_b32 s10, v248, 8
	v_readlane_b32 s11, v248, 9
	v_readlane_b32 s12, v248, 10
	v_readlane_b32 s13, v248, 11
	v_readlane_b32 s14, v248, 12
	v_readlane_b32 s15, v248, 13
	v_readlane_b32 s16, v248, 14
	v_readlane_b32 s17, v248, 15
	v_readlane_b32 s18, v248, 16
	v_readlane_b32 s19, v248, 17
	v_readlane_b32 s20, v248, 18
	v_readlane_b32 s21, v248, 19
	v_readlane_b32 s22, v248, 20
	v_readlane_b32 s23, v248, 21
	v_readlane_b32 s24, v248, 22
	v_readlane_b32 s25, v248, 23
	v_readlane_b32 s26, v248, 24
	v_readlane_b32 s27, v248, 25
	v_readlane_b32 s28, v248, 26
	v_readlane_b32 s29, v248, 27
	v_readlane_b32 s30, v248, 28
	v_readlane_b32 s31, v248, 29
	v_readlane_b32 s32, v248, 30
	v_readlane_b32 s33, v248, 31
	v_readlane_b32 s34, v248, 32
	v_readlane_b32 s35, v248, 33
	v_readlane_b32 s36, v248, 34
	v_readlane_b32 s37, v248, 35
	v_readlane_b32 s38, v248, 36
	v_readlane_b32 s39, v248, 37
	v_readlane_b32 s40, v248, 38
	v_readlane_b32 s41, v248, 39
	v_readlane_b32 s42, v248, 40
	v_readlane_b32 s43, v248, 41
	v_readlane_b32 s44, v248, 42
	v_readlane_b32 s45, v248, 43
	v_readlane_b32 s46, v248, 44
	v_readlane_b32 s47, v248, 45
	v_readlane_b32 s48, v248, 46
	v_readlane_b32 s49, v248, 47
	v_readlane_b32 s50, v248, 48
	v_readlane_b32 s51, v248, 49
	v_readlane_b32 s52, v248, 50
	v_readlane_b32 s53, v248, 51
	v_readlane_b32 s54, v248, 52
	v_readlane_b32 s55, v248, 53
	v_readlane_b32 s56, v248, 54
	v_readlane_b32 s57, v248, 55
	v_readlane_b32 s58, v248, 56
	v_readlane_b32 s59, v248, 57
	v_readlane_b32 s60, v248, 58
	v_readlane_b32 s61, v248, 59
	v_readlane_b32 s62, v248, 60
	v_readlane_b32 s63, v248, 61
	v_readlane_b32 s64, v248, 62
	v_readlane_b32 s65, v248, 63
	v_readlane_b32 s66, v249, 0
	v_readlane_b32 s67, v249, 1
	v_readlane_b32 s68, v249, 2
	v_readlane_b32 s69, v249, 3
	v_readlane_b32 s70, v249, 4
	v_readlane_b32 s71, v249, 5
	v_readlane_b32 s72, v249, 6
	v_readlane_b32 s73, v249, 7
	v_readlane_b32 s74, v249, 8
	v_readlane_b32 s75, v249, 9
	v_readlane_b32 s76, v249, 10
	v_readlane_b32 s77, v249, 11
	v_readlane_b32 s78, v249, 12
	v_readlane_b32 s79, v249, 13
	v_readlane_b32 s80, v249, 14
	s_waitcnt lgkmcnt(0)
	s_barrier
	s_branch .LBB0_641

; #define ATT_WAIT_TILE() do { if (FOX) { if (w == 0) asm volatile("s_waitcnt vmcnt(3)" ::: "memory"); else asm volatile("s_waitcnt vmcnt(2)" ::: "memory"); } \
;                              else asm volatile("s_waitcnt vmcnt(5)" ::: "memory"); } while (0)
; template <int DQK, int DV, bool FOX> ...
;     ...
;     { const bf16_t* qp = Q + (size_t)(q0 + 32 * w + r) * ldq + 8 * h;
; #pragma unroll
;       for (int d0 = 0; d0 < ND0; ++d0) qf[d0] = *(const bf16x8*)(qp + 16 * d0); }
;     float cq = 0.f, basev = 0.f;
;     if (FOX) {
;         const float tv = tot[lane]; float incl = tv;
; #pragma unroll
;         for (int o_ = 1; o_ < 64; o_ <<= 1) { const float t_ = __shfl_up(incl, o_); if (lane >= o_) incl += t_; }
;         basev = incl - tv;
;         cq = cum[q0 + 32 * w + r] + __builtin_bit_cast(float, __builtin_amdgcn_readlane(__builtin_bit_cast(int, basev), 4 * qb + (w >> 1)));
;     }
;     ...
;     const unsigned lds_u = (unsigned)(uintptr_t)lds;
;     f32x16 o[NCB];
; #pragma unroll
;     for (int cb = 0; cb < NCB; ++cb)
; #pragma unroll
;         for (int i = 0; i < 16; ++i) o[cb][i] = 0.f;
;     float mref = -1e30f, lsum = 0.f;
;     const int kread0 = r * KROW;
;     const int ksw = (r >> 1) & 7;
;     const int vread0 = KT_BYTES + ((lane >> 4) & 1) * 32 + (lane & 3) * 8 + (4 * h + ((lane & 15) >> 2)) * 64;
;     ...
;     ATT_DMA(0, 0); ATT_DMA(1, 1); ATT_WAIT_TILE(); __builtin_amdgcn_s_barrier();
; __global__ void __launch_bounds__(512, 2) fwd_kernel(Args a) {
;     ...
;         for (;;) {
;             if (tid == 0) *qw = atomicAdd(ctl + 64 * rep, 1u);
;             __syncthreads();
;             const unsigned idx = *qw;
;             __syncthreads();
;             if (idx >= 768u) break;
;             const int level = idx / 48, rr = idx % 48, qb = 15 - level;
.LBB0_647:
	s_or_b64 exec, exec, s[0:1]
	v_mov_b32_e32 v2, s38
	s_waitcnt vmcnt(0) lgkmcnt(0)
	s_barrier
	ds_read_b32 v2, v2
	s_movk_i32 s0, 0x39f
	s_waitcnt lgkmcnt(0)
	s_barrier
	v_cmp_lt_u32_e32 vcc, s0, v2
	v_readfirstlane_b32 s6, v2
	s_mov_b64 s[0:1], -1
	s_cbranch_vccnz .LBB0_642
	s_cmp_gt_u32 s6, 0x27f
	s_cbranch_scc1 .Ldq_tail
	s_and_b32 s0, s6, 3
	s_lshr_b32 s1, s6, 2
	s_cmp_eq_u32 s0, 3
	s_cbranch_scc1 .Lcv_unit
	s_mul_i32 s1, s1, 3
	s_add_i32 s6, s1, s0
	s_branch .Ldq_go
.Ldq_tail:
	s_sub_i32 s6, s6, 0xa0
.Ldq_go:
	s_and_b32 s0, s6, 0xffff
	s_mul_i32 s0, s0, 0xaaab
	s_lshr_b32 s0, s0, 21
	s_mul_i32 s1, s0, 48
	s_sub_i32 s1, s6, s1
	s_and_b32 s8, s1, 0xffff
	s_sub_i32 s39, 15, s0
	s_mov_b64 s[0:1], -1
	s_cmp_gt_u32 s8, 15
	v_lshlrev_b32_e32 v150, 1, v148
	v_lshlrev_b32_e32 v190, 1, v154
	s_cbranch_scc0 .LBB0_679
	s_add_i32 s84, s8, -16
	s_lshr_b32 s0, s84, 4
	s_mov_b32 s1, s85
	v_writelane_b32 v255, s0, 44
	v_mov_b32_e32 v5, v151
	v_and_b32_e32 v105, 64, v228
	v_writelane_b32 v255, s1, 45
	s_lshl_b64 s[0:1], s[0:1], 26
	v_readlane_b32 s2, v255, 16
	s_add_u32 s0, s2, s0
	v_readlane_b32 s2, v255, 17
	s_addc_u32 s1, s2, s1
	s_lshl_b32 s2, s8, 6
	s_and_b32 s2, s2, 0x3c0
	s_lshl_b32 s2, s2, 1
	v_writelane_b32 v255, s2, 46
	s_add_u32 s14, s0, s2
	s_addc_u32 s15, s1, 0
	s_lshl_b64 s[0:1], s[84:85], 14
	v_readlane_b32 s2, v255, 12
	s_add_u32 s16, s2, s0
	v_readlane_b32 s2, v255, 13
	s_addc_u32 s17, s2, s1
	v_readlane_b32 s2, v255, 22
	s_add_u32 s2, s2, s0
	v_readlane_b32 s0, v255, 23
	s_addc_u32 s3, s0, s1
	s_lshl_b32 s84, s84, 6
	v_lshl_add_u64 v[2:3], s[84:85], 2, v[152:153]
	global_load_dword v3, v[2:3], off
	v_readfirstlane_b32 s1, v0
	s_lshr_b32 s7, s1, 6
	s_lshl_b32 s0, s39, 8
	s_lshl_b32 s4, s7, 5
	s_add_i32 s0, s4, s0
	v_or_b32_e32 v4, s0, v146
	v_lshlrev_b64 v[8:9], 14, v[4:5]
	v_lshl_add_u64 v[4:5], v[4:5], 2, s[16:17]
	v_lshl_add_u64 v[8:9], s[14:15], 0, v[8:9]
	global_load_dword v10, v[4:5], off
	v_lshl_add_u64 v[4:5], v[8:9], 0, v[150:151]
	global_load_dwordx4 v[66:69], v[4:5], off
	global_load_dwordx4 v[70:73], v[4:5], off offset:32
	global_load_dwordx4 v[74:77], v[4:5], off offset:64
	global_load_dwordx4 v[78:81], v[4:5], off offset:96
	v_add_u32_e32 v6, -1, v228
	v_add_u32_e32 v11, -2, v228
	v_cmp_lt_i32_e32 vcc, v6, v105
	v_add_u32_e32 v12, -4, v228
	v_add_u32_e32 v13, -8, v228
	v_cndmask_b32_e32 v4, v6, v228, vcc
	v_cmp_lt_i32_e32 vcc, v11, v105
	v_add_u32_e32 v14, -16, v228
	v_subrev_u32_e32 v15, 32, v228
	v_cndmask_b32_e32 v5, v11, v228, vcc
	v_cmp_lt_i32_e32 vcc, v12, v105
	s_and_b32 s16, s1, 0xffffffc0
	s_lshr_b32 s9, s1, 2
	v_cndmask_b32_e32 v6, v12, v228, vcc
	v_cmp_lt_i32_e32 vcc, v13, v105
	v_lshlrev_b32_e32 v12, 2, v4
	v_and_or_b32 v4, s9, 48, v155
	v_cndmask_b32_e32 v8, v13, v228, vcc
	v_cmp_lt_i32_e32 vcc, v14, v105
	v_mov_b32_e32 v7, v151
	v_lshlrev_b32_e32 v13, 2, v5
	v_cndmask_b32_e32 v9, v14, v228, vcc
	v_cmp_lt_i32_e32 vcc, v15, v105
	v_lshlrev_b32_e32 v14, 2, v6
	v_lshlrev_b32_e32 v6, 14, v4
	v_cndmask_b32_e32 v11, v15, v228, vcc
	v_or_b32_e32 v15, s16, v196
	v_ashrrev_i32_e32 v5, 31, v15
	v_lshrrev_b32_e32 v16, 29, v5
	v_lshl_add_u64 v[4:5], s[14:15], 0, v[6:7]
	s_mov_b64 s[18:19], 0x1000
	v_lshl_add_u64 v[4:5], v[4:5], 0, s[18:19]
	v_readlane_b32 s18, v255, 24
	v_readlane_b32 s19, v255, 25
	v_lshlrev_b32_e32 v8, 2, v8
	v_add_u32_e32 v7, v15, v16
	v_lshlrev_b32_e32 v9, 2, v9
	v_lshlrev_b32_e32 v11, 2, v11
	s_lshr_b32 s17, s1, 3
	s_lshl_b32 s33, s7, 10
	s_lshl_b32 s5, s39, 2
	s_lshr_b32 s11, s1, 7
	s_and_b32 s7, s17, 0x1fffffe0
	s_add_i32 s33, s33, 0
	s_add_i32 s11, s11, s5
	s_lshl_b32 s84, s7, 1
	s_add_i32 s9, s33, 0x2000
	s_mov_b64 s[20:21], 0x800
	s_cmp_lt_u32 s1, 64
	v_mov_b32_e32 v191, v151
	v_lshl_add_u64 v[4:5], v[4:5], 0, s[84:85]
	s_cselect_b64 s[96:97], -1, 0
	s_cmp_gt_u32 s1, 63
	v_lshl_add_u64 v[4:5], v[4:5], 0, v[190:191]
	s_cselect_b64 s[92:93], -1, 0
	v_lshlrev_b32_e32 v2, 2, v196
	s_and_b64 vcc, exec, s[92:93]
	s_waitcnt vmcnt(5)
	ds_bpermute_b32 v6, v12, v3
	s_waitcnt lgkmcnt(0)
	v_add_f32_e32 v6, v3, v6
	v_cndmask_b32_e64 v12, v6, v3, s[18:19]
	ds_bpermute_b32 v13, v13, v12
	v_readlane_b32 s18, v255, 26
	v_readlane_b32 s19, v255, 27
	v_ashrrev_i32_e32 v6, 3, v7
	v_and_b32_e32 v7, 0x1ffffff8, v7
	s_waitcnt lgkmcnt(0)
	v_add_f32_e32 v13, v12, v13
	v_cndmask_b32_e64 v12, v13, v12, s[18:19]
	ds_bpermute_b32 v13, v14, v12
	v_readlane_b32 s18, v255, 28
	v_readlane_b32 s19, v255, 29
	v_sub_u32_e32 v14, v15, v7
	v_lshrrev_b32_e32 v15, 1, v6
	s_waitcnt lgkmcnt(0)
	v_add_f32_e32 v13, v12, v13
	v_cndmask_b32_e64 v12, v13, v12, s[18:19]
	ds_bpermute_b32 v8, v8, v12
	v_readlane_b32 s18, v255, 30
	v_readlane_b32 s19, v255, 31
	v_bitop3_b32 v13, v15, v14, 7 bitop3:0x6c
	v_ashrrev_i32_e32 v7, 31, v6
	s_waitcnt lgkmcnt(0)
	v_add_f32_e32 v8, v12, v8
	v_cndmask_b32_e64 v12, v8, v12, s[18:19]
	ds_bpermute_b32 v14, v9, v12
	v_lshlrev_b64 v[6:7], 14, v[6:7]
	v_lshl_add_u64 v[6:7], s[14:15], 0, v[6:7]
	v_readlane_b32 s14, v255, 32
	v_lshlrev_b32_e32 v8, 3, v13
	s_waitcnt lgkmcnt(0)
	v_add_f32_e32 v13, v12, v14
	v_readlane_b32 s15, v255, 33
	v_ashrrev_i32_e32 v9, 31, v8
	v_lshl_add_u64 v[8:9], v[8:9], 1, v[6:7]
	v_cndmask_b32_e64 v12, v13, v12, s[14:15]
	ds_bpermute_b32 v11, v11, v12
	v_lshl_add_u64 v[6:7], v[8:9], 0, s[20:21]
	s_mov_b32 s1, m0
	s_mov_b32 m0, s33
	s_nop 0
	global_load_lds_dwordx4 v[6:7], off
	s_mov_b32 m0, s1
	s_waitcnt lgkmcnt(0)
	v_add_f32_e32 v11, v12, v11
	s_mov_b32 s1, m0
	s_mov_b32 m0, s9
	s_nop 0
	global_load_lds_dwordx4 v[4:5], off
	s_mov_b32 m0, s1
	v_cndmask_b32_e64 v11, v11, v12, s[12:13]
	v_sub_f32_e32 v107, v11, v3
	s_nop 0
	v_readlane_b32 s17, v107, s11
	s_cbranch_vccnz .LBB0_651
	v_mov_b32_e32 v3, v151
	v_lshl_add_u64 v[12:13], s[2:3], 0, v[2:3]
	v_readlane_b32 s7, v255, 34
	s_mov_b32 s1, m0
	s_mov_b32 m0, s7
	s_nop 0
	global_load_lds_dword v[12:13], off
	s_mov_b32 m0, s1
